# v009 plus: K staging writes issued before the last P.V group, exp2 of the second half of the H1 probabilities moved into the read-latency window of the next QK^T block
# baseline (speedup 1.0000x reference)
.Lh1_nomask:
	s_add_i32 s10, s54, 0xffffff81
	s_cmp_gt_i32 s10, s5
	s_cbranch_scc1 .Lh1_nopv
	ds_read_b64_tr_b16 v[236:237], v190 offset:0
	ds_read_b64_tr_b16 v[238:239], v190 offset:2048
	ds_read_b64_tr_b16 v[240:241], v190 offset:4096
	ds_read_b64_tr_b16 v[242:243], v190 offset:6144
	ds_read_b64_tr_b16 v[246:247], v190 offset:8192
	ds_read_b64_tr_b16 v[248:249], v190 offset:10240
	ds_read_b64_tr_b16 v[250:251], v190 offset:12288
	ds_read_b64_tr_b16 v[252:253], v190 offset:14336
	v_max_f32_e32 v15, v113, v113
	v_max_f32_e32 v17, v112, v112
	v_max_f32_e32 v15, v17, v15
	v_max3_f32 v15, v15, v114, v115
	v_max3_f32 v15, v15, v116, v117
	v_max3_f32 v15, v15, v118, v119
	v_max3_f32 v15, v15, v120, v121
	v_max3_f32 v15, v15, v122, v123
	v_max3_f32 v15, v15, v124, v125
	v_max3_f32 v15, v15, v126, v127
	v_max3_f32 v15, v15, v96, v97
	v_max3_f32 v15, v15, v98, v99
	v_max3_f32 v15, v15, v100, v101
	v_max3_f32 v15, v15, v102, v103
	v_max3_f32 v15, v15, v104, v105
	v_max3_f32 v15, v15, v106, v107
	v_max3_f32 v15, v15, v108, v109
	v_max3_f32 v15, v15, v110, v111
	s_waitcnt lgkmcnt(6)
	v_mfma_f32_32x32x16_bf16 v[80:95], v[18:21], v[236:239], v[80:95]
	ds_read_b64_tr_b16 v[236:237], v190 offset:512
	ds_read_b64_tr_b16 v[238:239], v190 offset:2560
	v_mov_b32_e32 v17, v15
	s_nop 1
	v_permlane32_swap_b32_e32 v15, v17
	v_max_f32_e32 v17, v17, v17
	s_waitcnt lgkmcnt(6)
	v_mfma_f32_32x32x16_bf16 v[80:95], v[22:25], v[240:243], v[80:95]
	ds_read_b64_tr_b16 v[240:241], v190 offset:4608
	ds_read_b64_tr_b16 v[242:243], v190 offset:6656
	v_max_f32_e32 v15, v15, v15
	v_max_f32_e32 v15, v15, v17
	v_sub_f32_e32 v17, v15, v208
	v_mul_f32_e32 v17, 0x3d93cd3a, v17
	s_waitcnt lgkmcnt(6)
	v_mfma_f32_32x32x16_bf16 v[80:95], v[26:29], v[246:249], v[80:95]
	ds_read_b64_tr_b16 v[246:247], v190 offset:8704
	ds_read_b64_tr_b16 v[248:249], v190 offset:10752
	v_cmp_ge_f32_e32 vcc, s86, v17
	v_max_f32_e32 v17, v208, v208
	v_max_f32_e32 v17, v17, v15
	v_sub_f32_e32 v15, v208, v17
	s_waitcnt lgkmcnt(6)
	v_mfma_f32_32x32x16_bf16 v[80:95], v[168:171], v[250:253], v[80:95]
	ds_read_b64_tr_b16 v[250:251], v190 offset:12800
	ds_read_b64_tr_b16 v[252:253], v190 offset:14848
	v_mul_f32_e32 v15, 0x3dd53b94, v15
	v_exp_f32_e32 v15, v15
	s_cmp_eq_u64 vcc, exec
	s_cselect_b64 s[10:11], -1, 0
	s_waitcnt lgkmcnt(6)
	v_mfma_f32_32x32x16_bf16 v[64:79], v[18:21], v[236:239], v[64:79]
	ds_read_b64_tr_b16 v[236:237], v190 offset:1024
	ds_read_b64_tr_b16 v[238:239], v190 offset:3072
	v_cndmask_b32_e64 v180, v17, v208, s[10:11]
	v_cndmask_b32_e64 v15, v15, 1.0, s[10:11]
	v_mul_f32_e32 v219, 0xbdd53b94, v180
	v_fmamk_f32 v216, v112, 0x3dd53b94, v219
	s_waitcnt lgkmcnt(6)
	v_mfma_f32_32x32x16_bf16 v[64:79], v[22:25], v[240:243], v[64:79]
	ds_read_b64_tr_b16 v[240:241], v190 offset:5120
	ds_read_b64_tr_b16 v[242:243], v190 offset:7168
	v_fmamk_f32 v218, v113, 0x3dd53b94, v219
	v_fmamk_f32 v214, v114, 0x3dd53b94, v219
	v_fmamk_f32 v217, v115, 0x3dd53b94, v219
	v_fmamk_f32 v212, v116, 0x3dd53b94, v219
	s_waitcnt lgkmcnt(6)
	v_mfma_f32_32x32x16_bf16 v[64:79], v[26:29], v[246:249], v[64:79]
	ds_read_b64_tr_b16 v[246:247], v190 offset:9216
	ds_read_b64_tr_b16 v[248:249], v190 offset:11264
	v_fmamk_f32 v215, v117, 0x3dd53b94, v219
	v_fmamk_f32 v211, v118, 0x3dd53b94, v219
	v_fmamk_f32 v213, v119, 0x3dd53b94, v219
	s_waitcnt lgkmcnt(6)
	v_mfma_f32_32x32x16_bf16 v[64:79], v[168:171], v[250:253], v[64:79]
	ds_read_b64_tr_b16 v[250:251], v190 offset:13312
	ds_read_b64_tr_b16 v[252:253], v190 offset:15360
	v_fmamk_f32 v182, v120, 0x3dd53b94, v219
	v_fmamk_f32 v208, v121, 0x3dd53b94, v219
	v_fmamk_f32 v183, v123, 0x3dd53b94, v219
	s_waitcnt lgkmcnt(6)
	v_mfma_f32_32x32x16_bf16 v[48:63], v[18:21], v[236:239], v[48:63]
	ds_read_b64_tr_b16 v[236:237], v190 offset:1536
	ds_read_b64_tr_b16 v[238:239], v190 offset:3584
	v_fmamk_f32 v181, v125, 0x3dd53b94, v219
	v_exp_f32_e32 v216, v216
	v_fmamk_f32 v220, v96, 0x3dd53b94, v219
	s_waitcnt lgkmcnt(6)
	v_mfma_f32_32x32x16_bf16 v[48:63], v[22:25], v[240:243], v[48:63]
	ds_read_b64_tr_b16 v[240:241], v190 offset:5632
	ds_read_b64_tr_b16 v[242:243], v190 offset:7680
	v_exp_f32_e32 v218, v218
	v_fmamk_f32 v221, v97, 0x3dd53b94, v219
	v_exp_f32_e32 v214, v214
	s_waitcnt lgkmcnt(6)
	v_mfma_f32_32x32x16_bf16 v[48:63], v[26:29], v[246:249], v[48:63]
	ds_read_b64_tr_b16 v[246:247], v190 offset:9728
	ds_read_b64_tr_b16 v[248:249], v190 offset:11776
	v_fmamk_f32 v222, v98, 0x3dd53b94, v219
	v_exp_f32_e32 v217, v217
	v_fmamk_f32 v223, v99, 0x3dd53b94, v219
	s_waitcnt lgkmcnt(6)
	v_mfma_f32_32x32x16_bf16 v[48:63], v[168:171], v[250:253], v[48:63]
	ds_read_b64_tr_b16 v[250:251], v190 offset:13824
	ds_read_b64_tr_b16 v[252:253], v190 offset:15872
	v_exp_f32_e32 v212, v212
	v_fmamk_f32 v224, v100, 0x3dd53b94, v219
	v_exp_f32_e32 v215, v215
	s_waitcnt vmcnt(0)
	ds_write_b128 v202, v[6:9] offset:32768
	ds_write_b128 v202, v[160:163] offset:45056
	ds_write_b128 v203, v[164:167] offset:32768
	s_waitcnt lgkmcnt(9)
	v_mfma_f32_32x32x16_bf16 v[32:47], v[18:21], v[236:239], v[32:47]
	v_fmamk_f32 v225, v101, 0x3dd53b94, v219
	v_exp_f32_e32 v211, v211
	v_fmamk_f32 v226, v102, 0x3dd53b94, v219
	s_waitcnt lgkmcnt(7)
	v_mfma_f32_32x32x16_bf16 v[32:47], v[22:25], v[240:243], v[32:47]
	v_exp_f32_e32 v213, v213
	v_fmamk_f32 v227, v103, 0x3dd53b94, v219
	v_fmamk_f32 v228, v104, 0x3dd53b94, v219
	s_waitcnt lgkmcnt(5)
	v_mfma_f32_32x32x16_bf16 v[32:47], v[26:29], v[246:249], v[32:47]
	v_fmamk_f32 v229, v105, 0x3dd53b94, v219
	v_fmamk_f32 v230, v106, 0x3dd53b94, v219
	v_fmamk_f32 v231, v107, 0x3dd53b94, v219
	s_waitcnt lgkmcnt(3)
	v_mfma_f32_32x32x16_bf16 v[32:47], v[168:171], v[250:253], v[32:47]
	v_fmamk_f32 v232, v108, 0x3dd53b94, v219
	v_fmamk_f32 v233, v109, 0x3dd53b94, v219
	v_fmamk_f32 v234, v110, 0x3dd53b94, v219
	s_branch .Lh1_post
.Lh1_nopv:
	v_max_f32_e32 v15, v113, v113
	v_max_f32_e32 v17, v112, v112
	v_max_f32_e32 v15, v17, v15
	v_max3_f32 v15, v15, v114, v115
	v_max3_f32 v15, v15, v116, v117
	v_max3_f32 v15, v15, v118, v119
	v_max3_f32 v15, v15, v120, v121
	v_max3_f32 v15, v15, v122, v123
	v_max3_f32 v15, v15, v124, v125
	v_max3_f32 v15, v15, v126, v127
	v_max3_f32 v15, v15, v96, v97
	v_max3_f32 v15, v15, v98, v99
	v_max3_f32 v15, v15, v100, v101
	v_max3_f32 v15, v15, v102, v103
	v_max3_f32 v15, v15, v104, v105
	v_max3_f32 v15, v15, v106, v107
	v_max3_f32 v15, v15, v108, v109
	v_max3_f32 v15, v15, v110, v111
	v_mov_b32_e32 v17, v15
	s_nop 1
	v_permlane32_swap_b32_e32 v15, v17
	v_max_f32_e32 v17, v17, v17
	v_max_f32_e32 v15, v15, v15
	v_max_f32_e32 v15, v15, v17
	v_sub_f32_e32 v17, v15, v208
	v_mul_f32_e32 v17, 0x3d93cd3a, v17
	v_cmp_ge_f32_e32 vcc, s86, v17
	v_max_f32_e32 v17, v208, v208
	v_max_f32_e32 v17, v17, v15
	v_sub_f32_e32 v15, v208, v17
	v_mul_f32_e32 v15, 0x3dd53b94, v15
	v_exp_f32_e32 v15, v15
	s_cmp_eq_u64 vcc, exec
	s_cselect_b64 s[10:11], -1, 0
	v_cndmask_b32_e64 v180, v17, v208, s[10:11]
	v_cndmask_b32_e64 v15, v15, 1.0, s[10:11]
	v_mul_f32_e32 v219, 0xbdd53b94, v180
	v_fmamk_f32 v216, v112, 0x3dd53b94, v219
	v_fmamk_f32 v218, v113, 0x3dd53b94, v219
	v_fmamk_f32 v214, v114, 0x3dd53b94, v219
	v_fmamk_f32 v217, v115, 0x3dd53b94, v219
	v_fmamk_f32 v212, v116, 0x3dd53b94, v219
	v_fmamk_f32 v215, v117, 0x3dd53b94, v219
	v_fmamk_f32 v211, v118, 0x3dd53b94, v219
	v_fmamk_f32 v213, v119, 0x3dd53b94, v219
	v_fmamk_f32 v182, v120, 0x3dd53b94, v219
	v_fmamk_f32 v208, v121, 0x3dd53b94, v219
	v_fmamk_f32 v183, v123, 0x3dd53b94, v219
	v_fmamk_f32 v181, v125, 0x3dd53b94, v219
	v_exp_f32_e32 v216, v216
	v_fmamk_f32 v220, v96, 0x3dd53b94, v219
	v_exp_f32_e32 v218, v218
	v_fmamk_f32 v221, v97, 0x3dd53b94, v219
	v_exp_f32_e32 v214, v214
	v_fmamk_f32 v222, v98, 0x3dd53b94, v219
	v_exp_f32_e32 v217, v217
	v_fmamk_f32 v223, v99, 0x3dd53b94, v219
	v_exp_f32_e32 v212, v212
	v_fmamk_f32 v224, v100, 0x3dd53b94, v219
	v_exp_f32_e32 v215, v215
	v_fmamk_f32 v225, v101, 0x3dd53b94, v219
	v_exp_f32_e32 v211, v211
	v_fmamk_f32 v226, v102, 0x3dd53b94, v219
	v_exp_f32_e32 v213, v213
	v_fmamk_f32 v227, v103, 0x3dd53b94, v219
	v_fmamk_f32 v228, v104, 0x3dd53b94, v219
	v_fmamk_f32 v229, v105, 0x3dd53b94, v219
	v_fmamk_f32 v230, v106, 0x3dd53b94, v219
	v_fmamk_f32 v231, v107, 0x3dd53b94, v219
	v_fmamk_f32 v232, v108, 0x3dd53b94, v219
	v_fmamk_f32 v233, v109, 0x3dd53b94, v219
	v_fmamk_f32 v234, v110, 0x3dd53b94, v219
	s_waitcnt vmcnt(0)
	ds_write_b128 v202, v[6:9] offset:32768
	ds_write_b128 v202, v[160:163] offset:45056
	ds_write_b128 v203, v[164:167] offset:32768
.Lh1_post:
	v_cmp_gt_f32_e32 vcc, 1.0, v15
	s_cbranch_vccz .Lh1_norsc
	s_and_saveexec_b64 s[78:79], s[8:9]
	ds_write_b32 v192, v15 offset:128
	s_or_b64 exec, exec, s[78:79]
	s_waitcnt lgkmcnt(0)
	ds_read_b128 v[18:21], v189 offset:224
	ds_read_b128 v[22:25], v189 offset:192
	ds_read_b128 v[26:29], v189 offset:160
	ds_read_b128 v[168:171], v189 offset:128
	s_waitcnt lgkmcnt(3)
	v_pk_mul_f32 v[94:95], v[94:95], v[20:21]
	s_waitcnt lgkmcnt(2)
	v_pk_mul_f32 v[90:91], v[90:91], v[24:25]
	s_waitcnt lgkmcnt(1)
	v_pk_mul_f32 v[86:87], v[86:87], v[28:29]
	s_waitcnt lgkmcnt(0)
	v_pk_mul_f32 v[82:83], v[82:83], v[170:171]
	v_pk_mul_f32 v[92:93], v[92:93], v[18:19]
	v_pk_mul_f32 v[88:89], v[88:89], v[22:23]
	v_pk_mul_f32 v[84:85], v[84:85], v[26:27]
	v_pk_mul_f32 v[80:81], v[80:81], v[168:169]
	v_pk_mul_f32 v[78:79], v[78:79], v[20:21]
	v_pk_mul_f32 v[74:75], v[74:75], v[24:25]
	v_pk_mul_f32 v[70:71], v[70:71], v[28:29]
	v_pk_mul_f32 v[66:67], v[66:67], v[170:171]
	v_pk_mul_f32 v[76:77], v[76:77], v[18:19]
	v_pk_mul_f32 v[72:73], v[72:73], v[22:23]
	v_pk_mul_f32 v[68:69], v[68:69], v[26:27]
	v_pk_mul_f32 v[64:65], v[64:65], v[168:169]
	v_pk_mul_f32 v[62:63], v[62:63], v[20:21]
	v_pk_mul_f32 v[58:59], v[58:59], v[24:25]
	v_pk_mul_f32 v[54:55], v[54:55], v[28:29]
	v_pk_mul_f32 v[50:51], v[50:51], v[170:171]
	v_pk_mul_f32 v[60:61], v[60:61], v[18:19]
	v_pk_mul_f32 v[56:57], v[56:57], v[22:23]
	v_pk_mul_f32 v[52:53], v[52:53], v[26:27]
	v_pk_mul_f32 v[48:49], v[48:49], v[168:169]
	v_pk_mul_f32 v[46:47], v[46:47], v[20:21]
	v_pk_mul_f32 v[42:43], v[42:43], v[24:25]
	v_pk_mul_f32 v[38:39], v[38:39], v[28:29]
	v_pk_mul_f32 v[34:35], v[34:35], v[170:171]
	v_pk_mul_f32 v[44:45], v[44:45], v[18:19]
	v_pk_mul_f32 v[40:41], v[40:41], v[22:23]
	v_pk_mul_f32 v[36:37], v[36:37], v[26:27]
	v_pk_mul_f32 v[32:33], v[32:33], v[168:169]
.Lh1_norsc:
	v_fmamk_f32 v171, v122, 0x3dd53b94, v219
	v_fmamk_f32 v169, v124, 0x3dd53b94, v219
	v_fmamk_f32 v168, v126, 0x3dd53b94, v219
	v_fmamk_f32 v170, v127, 0x3dd53b94, v219
	v_fmac_f32_e32 v219, 0x3dd53b94, v111
	s_add_i32 s10, s54, 1
	s_waitcnt lgkmcnt(0)
	s_barrier
	ds_write_b128 v200, v[2:5]
	ds_write_b128 v201, v[10:13]
	s_cmp_gt_i32 s10, s5
	s_cbranch_scc1 .LBB0_407
	ds_read_b128 v[236:239], v196 offset:32768
	ds_read_b128 v[240:243], v196 offset:45056
	ds_read_b128 v[246:249], v197 offset:32768
	ds_read_b128 v[250:253], v197 offset:45056
	ds_read_b128 v[6:9], v195
	ds_read_b128 v[10:13], v195 offset:1024
	ds_read_b128 v[2:5], v195 offset:2048
	v_exp_f32_e32 v182, v182
	v_exp_f32_e32 v208, v208
	v_exp_f32_e32 v171, v171
	v_exp_f32_e32 v183, v183
	v_exp_f32_e32 v169, v169
	v_exp_f32_e32 v181, v181
	v_exp_f32_e32 v168, v168
	v_exp_f32_e32 v170, v170
	v_cvt_pk_bf16_f32 v18, v216, v218
	v_cvt_pk_bf16_f32 v19, v214, v217
	v_cvt_pk_bf16_f32 v20, v212, v215
	v_cvt_pk_bf16_f32 v21, v211, v213
	v_cvt_pk_bf16_f32 v22, v182, v208
	v_cvt_pk_bf16_f32 v23, v171, v183
	v_cvt_pk_bf16_f32 v24, v169, v181
	v_cvt_pk_bf16_f32 v25, v168, v170
	v_add_f32_e32 v17, 0, v216
	v_add_f32_e32 v17, v218, v17
	v_add_f32_e32 v17, v214, v17
	v_add_f32_e32 v17, v217, v17
	v_add_f32_e32 v17, v212, v17
	v_add_f32_e32 v17, v215, v17
	v_add_f32_e32 v17, v211, v17
	v_add_f32_e32 v17, v213, v17
	s_waitcnt lgkmcnt(6)
	v_mfma_f32_32x32x16_bf16 v[112:127], v[236:239], v[156:159], 0
	ds_read_b128 v[236:239], v199 offset:32768
	v_add_f32_e32 v17, v182, v17
	v_add_f32_e32 v17, v208, v17
	v_permlane32_swap_b32_e32 v18, v20
	s_waitcnt lgkmcnt(6)
	v_mfma_f32_32x32x16_bf16 v[96:111], v[240:243], v[156:159], 0
	ds_read_b128 v[240:243], v199 offset:45056
	v_add_f32_e32 v17, v171, v17
	v_add_f32_e32 v17, v183, v17
	v_permlane32_swap_b32_e32 v19, v21
	s_waitcnt lgkmcnt(6)
	v_mfma_f32_32x32x16_bf16 v[112:127], v[246:249], v[152:155], v[112:127]
	ds_read_b128 v[246:249], v198 offset:32768
	v_add_f32_e32 v17, v169, v17
	v_add_f32_e32 v17, v181, v17
	s_waitcnt lgkmcnt(6)
	v_mfma_f32_32x32x16_bf16 v[96:111], v[250:253], v[152:155], v[96:111]
	ds_read_b128 v[250:253], v198 offset:45056
	v_permlane32_swap_b32_e32 v22, v24
	v_add_f32_e32 v17, v168, v17
	s_waitcnt lgkmcnt(3)
	v_mfma_f32_32x32x16_bf16 v[112:127], v[236:239], v[148:151], v[112:127]
	ds_read_b128 v[236:239], v196 offset:32896
	v_add_f32_e32 v17, v170, v17
	v_permlane32_swap_b32_e32 v23, v25
	s_waitcnt lgkmcnt(3)
	v_mfma_f32_32x32x16_bf16 v[96:111], v[240:243], v[148:151], v[96:111]
	ds_read_b128 v[240:243], v196 offset:45184
	v_exp_f32_e32 v220, v220
	v_exp_f32_e32 v221, v221
	s_waitcnt lgkmcnt(3)
	v_mfma_f32_32x32x16_bf16 v[112:127], v[246:249], v[144:147], v[112:127]
	ds_read_b128 v[246:249], v197 offset:32896
	v_exp_f32_e32 v222, v222
	v_exp_f32_e32 v223, v223
	s_waitcnt lgkmcnt(3)
	v_mfma_f32_32x32x16_bf16 v[96:111], v[250:253], v[144:147], v[96:111]
	ds_read_b128 v[250:253], v197 offset:45184
	v_add_f32_e32 v17, v220, v17
	v_exp_f32_e32 v224, v224
	s_waitcnt lgkmcnt(3)
	v_mfma_f32_32x32x16_bf16 v[112:127], v[236:239], v[140:143], v[112:127]
	ds_read_b128 v[236:239], v199 offset:32896
	v_add_f32_e32 v17, v221, v17
	v_exp_f32_e32 v225, v225
	s_waitcnt lgkmcnt(3)
	v_mfma_f32_32x32x16_bf16 v[96:111], v[240:243], v[140:143], v[96:111]
	ds_read_b128 v[240:243], v199 offset:45184
	v_add_f32_e32 v17, v222, v17
	v_exp_f32_e32 v226, v226
	s_waitcnt lgkmcnt(3)
	v_mfma_f32_32x32x16_bf16 v[112:127], v[246:249], v[136:139], v[112:127]
	ds_read_b128 v[246:249], v198 offset:32896
	v_add_f32_e32 v17, v223, v17
	v_exp_f32_e32 v227, v227
	s_waitcnt lgkmcnt(3)
	v_mfma_f32_32x32x16_bf16 v[96:111], v[250:253], v[136:139], v[96:111]
	ds_read_b128 v[250:253], v198 offset:45184
	v_cvt_pk_bf16_f32 v26, v220, v221
	v_cvt_pk_bf16_f32 v27, v222, v223
	s_waitcnt lgkmcnt(3)
	v_mfma_f32_32x32x16_bf16 v[112:127], v[236:239], v[132:135], v[112:127]
	ds_read_b128 v[236:239], v196 offset:33024
	v_add_f32_e32 v17, v224, v17
	v_exp_f32_e32 v228, v228
	s_waitcnt lgkmcnt(3)
	v_mfma_f32_32x32x16_bf16 v[96:111], v[240:243], v[132:135], v[96:111]
	ds_read_b128 v[240:243], v196 offset:45312
	v_add_f32_e32 v17, v225, v17
	v_exp_f32_e32 v229, v229
	s_waitcnt lgkmcnt(3)
	v_mfma_f32_32x32x16_bf16 v[112:127], v[246:249], v[128:131], v[112:127]
	ds_read_b128 v[246:249], v197 offset:33024
	v_add_f32_e32 v17, v226, v17
	v_exp_f32_e32 v230, v230
	s_waitcnt lgkmcnt(3)
	v_mfma_f32_32x32x16_bf16 v[96:111], v[250:253], v[128:131], v[96:111]
	ds_read_b128 v[250:253], v197 offset:45312
	v_add_f32_e32 v17, v227, v17
	v_exp_f32_e32 v231, v231
	s_waitcnt lgkmcnt(3)
	v_mfma_f32_32x32x16_bf16 v[112:127], v[236:239], v[6:9], v[112:127]
	ds_read_b128 v[236:239], v199 offset:33024
	v_cvt_pk_bf16_f32 v28, v224, v225
	v_cvt_pk_bf16_f32 v29, v226, v227
	s_waitcnt lgkmcnt(3)
	v_mfma_f32_32x32x16_bf16 v[96:111], v[240:243], v[6:9], v[96:111]
	ds_read_b128 v[240:243], v199 offset:45312
	ds_read_b128 v[6:9], v195 offset:3072
	v_add_f32_e32 v17, v228, v17
	v_exp_f32_e32 v232, v232
	s_waitcnt lgkmcnt(4)
	v_mfma_f32_32x32x16_bf16 v[112:127], v[246:249], v[10:13], v[112:127]
	ds_read_b128 v[246:249], v198 offset:33024
	v_permlane32_swap_b32_e32 v26, v28
	v_permlane32_swap_b32_e32 v27, v29
	s_waitcnt lgkmcnt(4)
	v_mfma_f32_32x32x16_bf16 v[96:111], v[250:253], v[10:13], v[96:111]
	ds_read_b128 v[250:253], v198 offset:45312
	v_add_f32_e32 v17, v229, v17
	v_exp_f32_e32 v233, v233
	s_waitcnt lgkmcnt(4)
	v_mfma_f32_32x32x16_bf16 v[112:127], v[236:239], v[2:5], v[112:127]
	v_add_f32_e32 v17, v230, v17
	v_exp_f32_e32 v234, v234
	s_waitcnt lgkmcnt(3)
	v_mfma_f32_32x32x16_bf16 v[96:111], v[240:243], v[2:5], v[96:111]
	v_add_f32_e32 v17, v231, v17
	v_exp_f32_e32 v219, v219
	s_waitcnt lgkmcnt(1)
	v_mfma_f32_32x32x16_bf16 v[112:127], v[246:249], v[6:9], v[112:127]
	v_cvt_pk_bf16_f32 v168, v228, v229
	v_cvt_pk_bf16_f32 v169, v230, v231
	s_waitcnt lgkmcnt(0)
	v_mfma_f32_32x32x16_bf16 v[96:111], v[250:253], v[6:9], v[96:111]
	v_add_f32_e32 v17, v232, v17
	v_add_f32_e32 v17, v233, v17
	v_add_f32_e32 v17, v234, v17
	v_add_f32_e32 v17, v219, v17
	v_cvt_pk_bf16_f32 v170, v232, v233
	v_cvt_pk_bf16_f32 v171, v234, v219
	v_mov_b32_e32 v30, v17
	s_nop 1
	v_permlane32_swap_b32_e32 v168, v170
	v_permlane32_swap_b32_e32 v169, v171
	v_permlane32_swap_b32_e32 v17, v30
	s_branch .Lattn_h2_join
.LBB0_407:
	v_exp_f32_e32 v182, v182
	v_exp_f32_e32 v208, v208
	v_exp_f32_e32 v171, v171
	v_exp_f32_e32 v183, v183
	v_exp_f32_e32 v169, v169
	v_exp_f32_e32 v181, v181
	v_exp_f32_e32 v168, v168
	v_exp_f32_e32 v170, v170
	v_mov_b32_e32 v30, v16
	v_mov_b32_e32 v31, v16
	v_mov_b32_e32 v17, v16
	v_mov_b32_e32 v18, v16
	v_mov_b32_e32 v19, v16
	v_mov_b32_e32 v20, v16
	v_mov_b32_e32 v21, v16
	v_mov_b32_e32 v22, v16
	v_mov_b32_e32 v23, v16
	v_mov_b32_e32 v24, v16
	v_mov_b32_e32 v25, v16
	v_mov_b32_e32 v26, v16
	v_mov_b32_e32 v27, v16
	v_mov_b32_e32 v28, v16
	v_mov_b32_e32 v29, v16
	v_mov_b64_e32 v[126:127], v[30:31]
	v_mov_b64_e32 v[110:111], v[30:31]
	v_mov_b64_e32 v[124:125], v[28:29]
	v_mov_b64_e32 v[122:123], v[26:27]
	v_mov_b64_e32 v[120:121], v[24:25]
	v_mov_b64_e32 v[118:119], v[22:23]
	v_mov_b64_e32 v[116:117], v[20:21]
	v_mov_b64_e32 v[114:115], v[18:19]
	v_mov_b64_e32 v[112:113], v[16:17]
	v_mov_b64_e32 v[108:109], v[28:29]
	v_mov_b64_e32 v[106:107], v[26:27]
	v_mov_b64_e32 v[104:105], v[24:25]
	v_mov_b64_e32 v[102:103], v[22:23]
	v_mov_b64_e32 v[100:101], v[20:21]
	v_mov_b64_e32 v[98:99], v[18:19]
	v_mov_b64_e32 v[96:97], v[16:17]

.Lh2_nomask:
	s_andn2_b64 vcc, exec, s[76:77]
	s_cbranch_vccnz .Lh2_nopv
	ds_read_b64_tr_b16 v[236:237], v190 offset:16384
	ds_read_b64_tr_b16 v[238:239], v190 offset:18432
	ds_read_b64_tr_b16 v[240:241], v190 offset:20480
	ds_read_b64_tr_b16 v[242:243], v190 offset:22528
	ds_read_b64_tr_b16 v[246:247], v190 offset:24576
	ds_read_b64_tr_b16 v[248:249], v190 offset:26624
	ds_read_b64_tr_b16 v[250:251], v190 offset:28672
	ds_read_b64_tr_b16 v[252:253], v190 offset:30720
	v_max_f32_e32 v255, v113, v113
	v_max_f32_e32 v245, v112, v112
	v_max_f32_e32 v255, v245, v255
	v_max3_f32 v255, v255, v114, v115
	v_max3_f32 v255, v255, v116, v117
	v_max3_f32 v255, v255, v118, v119
	v_max3_f32 v255, v255, v120, v121
	v_max3_f32 v255, v255, v122, v123
	v_max3_f32 v255, v255, v124, v125
	v_max3_f32 v255, v255, v126, v127
	v_max3_f32 v255, v255, v96, v97
	v_max3_f32 v255, v255, v98, v99
	v_max3_f32 v255, v255, v100, v101
	v_max3_f32 v255, v255, v102, v103
	v_max3_f32 v255, v255, v104, v105
	v_max3_f32 v255, v255, v106, v107
	v_max3_f32 v255, v255, v108, v109
	v_max3_f32 v255, v255, v110, v111
	s_waitcnt lgkmcnt(6)
	v_mfma_f32_32x32x16_bf16 v[80:95], v[18:21], v[236:239], v[80:95]
	ds_read_b64_tr_b16 v[236:237], v190 offset:16896
	ds_read_b64_tr_b16 v[238:239], v190 offset:18944
	v_mov_b32_e32 v245, v255
	s_nop 1
	v_permlane32_swap_b32_e32 v255, v245
	v_max_f32_e32 v245, v245, v245
	s_waitcnt lgkmcnt(6)
	v_mfma_f32_32x32x16_bf16 v[80:95], v[22:25], v[240:243], v[80:95]
	ds_read_b64_tr_b16 v[240:241], v190 offset:20992
	ds_read_b64_tr_b16 v[242:243], v190 offset:23040
	v_max_f32_e32 v255, v255, v255
	v_max_f32_e32 v255, v255, v245
	v_sub_f32_e32 v245, v255, v180
	v_mul_f32_e32 v245, 0x3d93cd3a, v245
	s_waitcnt lgkmcnt(6)
	v_mfma_f32_32x32x16_bf16 v[80:95], v[26:29], v[246:249], v[80:95]
	ds_read_b64_tr_b16 v[246:247], v190 offset:25088
	ds_read_b64_tr_b16 v[248:249], v190 offset:27136
	v_cmp_ge_f32_e32 vcc, s86, v245
	s_cmp_eq_u64 vcc, exec
	s_cselect_b64 s[10:11], -1, 0
	v_max_f32_e32 v235, v180, v180
	s_waitcnt lgkmcnt(6)
	v_mfma_f32_32x32x16_bf16 v[80:95], v[168:171], v[250:253], v[80:95]
	ds_read_b64_tr_b16 v[250:251], v190 offset:29184
	ds_read_b64_tr_b16 v[252:253], v190 offset:31232
	v_max_f32_e32 v245, v235, v255
	v_sub_f32_e32 v235, v180, v245
	v_mul_f32_e32 v235, 0x3dd53b94, v235
	v_exp_f32_e32 v235, v235
	s_waitcnt lgkmcnt(6)
	v_mfma_f32_32x32x16_bf16 v[64:79], v[18:21], v[236:239], v[64:79]
	ds_read_b64_tr_b16 v[236:237], v190 offset:17408
	ds_read_b64_tr_b16 v[238:239], v190 offset:19456
	v_cndmask_b32_e64 v208, v245, v180, s[10:11]
	v_cndmask_b32_e64 v235, v235, 1.0, s[10:11]
	v_mul_f32_e32 v254, 0xbdd53b94, v208
	v_mov_b32_e32 v213, v254
	s_waitcnt lgkmcnt(6)
	v_mfma_f32_32x32x16_bf16 v[64:79], v[22:25], v[240:243], v[64:79]
	ds_read_b64_tr_b16 v[240:241], v190 offset:21504
	ds_read_b64_tr_b16 v[242:243], v190 offset:23552
	v_fmamk_f32 v224, v112, 0x3dd53b94, v254
	v_fmamk_f32 v226, v113, 0x3dd53b94, v254
	v_fmamk_f32 v222, v114, 0x3dd53b94, v254
	v_fmamk_f32 v225, v115, 0x3dd53b94, v254
	s_waitcnt lgkmcnt(6)
	v_mfma_f32_32x32x16_bf16 v[64:79], v[26:29], v[246:249], v[64:79]
	ds_read_b64_tr_b16 v[246:247], v190 offset:25600
	ds_read_b64_tr_b16 v[248:249], v190 offset:27648
	v_fmamk_f32 v220, v116, 0x3dd53b94, v254
	v_fmamk_f32 v223, v117, 0x3dd53b94, v254
	v_fmamk_f32 v219, v118, 0x3dd53b94, v254
	s_waitcnt lgkmcnt(6)
	v_mfma_f32_32x32x16_bf16 v[64:79], v[168:171], v[250:253], v[64:79]
	ds_read_b64_tr_b16 v[250:251], v190 offset:29696
	ds_read_b64_tr_b16 v[252:253], v190 offset:31744
	v_fmamk_f32 v221, v119, 0x3dd53b94, v254
	v_fmamk_f32 v216, v120, 0x3dd53b94, v254
	v_fmamk_f32 v218, v121, 0x3dd53b94, v254
	s_waitcnt lgkmcnt(6)
	v_mfma_f32_32x32x16_bf16 v[48:63], v[18:21], v[236:239], v[48:63]
	ds_read_b64_tr_b16 v[236:237], v190 offset:17920
	ds_read_b64_tr_b16 v[238:239], v190 offset:19968
	v_fmamk_f32 v214, v122, 0x3dd53b94, v254
	v_fmamk_f32 v217, v123, 0x3dd53b94, v254
	v_fmamk_f32 v212, v124, 0x3dd53b94, v254
	s_waitcnt lgkmcnt(6)
	v_mfma_f32_32x32x16_bf16 v[48:63], v[22:25], v[240:243], v[48:63]
	ds_read_b64_tr_b16 v[240:241], v190 offset:22016
	ds_read_b64_tr_b16 v[242:243], v190 offset:24064
	v_fmamk_f32 v215, v125, 0x3dd53b94, v254
	v_fmamk_f32 v211, v126, 0x3dd53b94, v254
	v_fmac_f32_e32 v213, 0x3dd53b94, v127
	s_waitcnt lgkmcnt(6)
	v_mfma_f32_32x32x16_bf16 v[48:63], v[26:29], v[246:249], v[48:63]
	ds_read_b64_tr_b16 v[246:247], v190 offset:26112
	ds_read_b64_tr_b16 v[248:249], v190 offset:28160
	v_exp_f32_e32 v224, v224
	v_exp_f32_e32 v226, v226
	v_exp_f32_e32 v222, v222
	s_waitcnt lgkmcnt(6)
	v_mfma_f32_32x32x16_bf16 v[48:63], v[168:171], v[250:253], v[48:63]
	ds_read_b64_tr_b16 v[250:251], v190 offset:30208
	ds_read_b64_tr_b16 v[252:253], v190 offset:32256
	v_exp_f32_e32 v225, v225
	v_exp_f32_e32 v220, v220
	v_exp_f32_e32 v223, v223
	s_andn2_b64 vcc, exec, s[78:79]
	s_cbranch_vccnz .Lh2_g3nokw
	s_waitcnt vmcnt(0)
	ds_write_b128 v209, v[6:9]
	ds_write_b128 v209, v[160:163] offset:12288
	ds_write_b128 v203, v[164:167] offset:57344
	s_waitcnt lgkmcnt(9)
	v_mfma_f32_32x32x16_bf16 v[32:47], v[18:21], v[236:239], v[32:47]
	v_exp_f32_e32 v219, v219
	v_exp_f32_e32 v221, v221
	v_exp_f32_e32 v216, v216
	s_waitcnt lgkmcnt(7)
	v_mfma_f32_32x32x16_bf16 v[32:47], v[22:25], v[240:243], v[32:47]
	v_exp_f32_e32 v218, v218
	v_exp_f32_e32 v214, v214
	v_exp_f32_e32 v217, v217
	s_waitcnt lgkmcnt(5)
	v_mfma_f32_32x32x16_bf16 v[32:47], v[26:29], v[246:249], v[32:47]
	v_exp_f32_e32 v212, v212
	v_exp_f32_e32 v215, v215
	v_exp_f32_e32 v211, v211
	s_waitcnt lgkmcnt(3)
	v_mfma_f32_32x32x16_bf16 v[32:47], v[168:171], v[250:253], v[32:47]
	v_exp_f32_e32 v213, v213
	v_pk_fma_f32 v[182:183], v[96:97], s[30:31], v[254:255] op_sel_hi:[1,0,0]
	v_pk_fma_f32 v[180:181], v[98:99], s[30:31], v[254:255] op_sel_hi:[1,0,0]
	s_branch .Lh2_post
.Lh2_g3nokw:
	s_waitcnt lgkmcnt(6)
	v_mfma_f32_32x32x16_bf16 v[32:47], v[18:21], v[236:239], v[32:47]
	v_exp_f32_e32 v219, v219
	v_exp_f32_e32 v221, v221
	v_exp_f32_e32 v216, v216
	s_waitcnt lgkmcnt(4)
	v_mfma_f32_32x32x16_bf16 v[32:47], v[22:25], v[240:243], v[32:47]
	v_exp_f32_e32 v218, v218
	v_exp_f32_e32 v214, v214
	v_exp_f32_e32 v217, v217
	s_waitcnt lgkmcnt(2)
	v_mfma_f32_32x32x16_bf16 v[32:47], v[26:29], v[246:249], v[32:47]
	v_exp_f32_e32 v212, v212
	v_exp_f32_e32 v215, v215
	v_exp_f32_e32 v211, v211
	s_waitcnt lgkmcnt(0)
	v_mfma_f32_32x32x16_bf16 v[32:47], v[168:171], v[250:253], v[32:47]
	v_exp_f32_e32 v213, v213
	v_pk_fma_f32 v[182:183], v[96:97], s[30:31], v[254:255] op_sel_hi:[1,0,0]
	v_pk_fma_f32 v[180:181], v[98:99], s[30:31], v[254:255] op_sel_hi:[1,0,0]
	s_branch .Lh2_post
.Lh2_nopv:
	v_max_f32_e32 v255, v113, v113
	v_max_f32_e32 v245, v112, v112
	v_max_f32_e32 v255, v245, v255
	v_max3_f32 v255, v255, v114, v115
	v_max3_f32 v255, v255, v116, v117
	v_max3_f32 v255, v255, v118, v119
	v_max3_f32 v255, v255, v120, v121
	v_max3_f32 v255, v255, v122, v123
	v_max3_f32 v255, v255, v124, v125
	v_max3_f32 v255, v255, v126, v127
	v_max3_f32 v255, v255, v96, v97
	v_max3_f32 v255, v255, v98, v99
	v_max3_f32 v255, v255, v100, v101
	v_max3_f32 v255, v255, v102, v103
	v_max3_f32 v255, v255, v104, v105
	v_max3_f32 v255, v255, v106, v107
	v_max3_f32 v255, v255, v108, v109
	v_max3_f32 v255, v255, v110, v111
	v_mov_b32_e32 v245, v255
	s_nop 1
	v_permlane32_swap_b32_e32 v255, v245
	v_max_f32_e32 v245, v245, v245
	v_max_f32_e32 v255, v255, v255
	v_max_f32_e32 v255, v255, v245
	v_sub_f32_e32 v245, v255, v180
	v_mul_f32_e32 v245, 0x3d93cd3a, v245
	v_cmp_ge_f32_e32 vcc, s86, v245
	s_cmp_eq_u64 vcc, exec
	s_cselect_b64 s[10:11], -1, 0
	v_max_f32_e32 v235, v180, v180
	v_max_f32_e32 v245, v235, v255
	v_sub_f32_e32 v235, v180, v245
	v_mul_f32_e32 v235, 0x3dd53b94, v235
	v_exp_f32_e32 v235, v235
	v_cndmask_b32_e64 v208, v245, v180, s[10:11]
	v_cndmask_b32_e64 v235, v235, 1.0, s[10:11]
	v_mul_f32_e32 v254, 0xbdd53b94, v208
	v_mov_b32_e32 v213, v254
	v_fmamk_f32 v224, v112, 0x3dd53b94, v254
	v_fmamk_f32 v226, v113, 0x3dd53b94, v254
	v_fmamk_f32 v222, v114, 0x3dd53b94, v254
	v_fmamk_f32 v225, v115, 0x3dd53b94, v254
	v_fmamk_f32 v220, v116, 0x3dd53b94, v254
	v_fmamk_f32 v223, v117, 0x3dd53b94, v254
	v_fmamk_f32 v219, v118, 0x3dd53b94, v254
	v_fmamk_f32 v221, v119, 0x3dd53b94, v254
	v_fmamk_f32 v216, v120, 0x3dd53b94, v254
	v_fmamk_f32 v218, v121, 0x3dd53b94, v254
	v_fmamk_f32 v214, v122, 0x3dd53b94, v254
	v_fmamk_f32 v217, v123, 0x3dd53b94, v254
	v_fmamk_f32 v212, v124, 0x3dd53b94, v254
	v_fmamk_f32 v215, v125, 0x3dd53b94, v254
	v_fmamk_f32 v211, v126, 0x3dd53b94, v254
	v_fmac_f32_e32 v213, 0x3dd53b94, v127
	v_exp_f32_e32 v224, v224
	v_exp_f32_e32 v226, v226
	v_exp_f32_e32 v222, v222
	v_exp_f32_e32 v225, v225
	v_exp_f32_e32 v220, v220
	v_exp_f32_e32 v223, v223
	v_exp_f32_e32 v219, v219
	v_exp_f32_e32 v221, v221
	v_exp_f32_e32 v216, v216
	v_exp_f32_e32 v218, v218
	v_exp_f32_e32 v214, v214
	v_exp_f32_e32 v217, v217
	v_exp_f32_e32 v212, v212
	v_exp_f32_e32 v215, v215
	v_exp_f32_e32 v211, v211
	v_exp_f32_e32 v213, v213
	v_pk_fma_f32 v[182:183], v[96:97], s[30:31], v[254:255] op_sel_hi:[1,0,0]
	v_pk_fma_f32 v[180:181], v[98:99], s[30:31], v[254:255] op_sel_hi:[1,0,0]
	s_andn2_b64 vcc, exec, s[78:79]
	s_cbranch_vccnz .Lh2_post
	s_waitcnt vmcnt(0)
	ds_write_b128 v209, v[6:9]
	ds_write_b128 v209, v[160:163] offset:12288
	ds_write_b128 v203, v[164:167] offset:57344
